# speedup vs baseline: 1.0151x; 1.0065x over previous
; __device__ __forceinline__ void epilogue(const Params& p, int mode, const float* resid, int r, int c, f32x4 v) {
;   if (mode == EPI_PROJ) {
;     if (r >= INW) return;
;     u32x2 pk = {pk2(v[0], v[1]), pk2(v[2], v[3])};
;     *reinterpret_cast<u32x2*>(WSP(u16, WS_PROJB) + (long)c * INWP + r) = pk;
;   } else if (mode == EPI_PROJ_T) {
;     const int b = r >> 11, t = r & 2047;
;     u16* tp;
;     if (c < OFF_RG) tp = WSP(u16, WS_RVT) + ((long)(b * 2048 + c - OFF_RV)) * 2048 + t;
;     else if (c < OFF_KW) tp = WSP(u16, WS_VST) + ((long)(b * 512 + c - OFF_VS)) * 2048 + t;
;     else tp = WSP(u16, WS_VWT) + ((long)(b * 512 + c - OFF_VW)) * 2048 + t;
;     *reinterpret_cast<u32x2*>(tp) = u32x2{pk2(v[0], v[1]), pk2(v[2], v[3])};
.LBB0_404:
	s_or_b64 exec, exec, s[0:1]
	v_add_u32_e32 v190, s74, v187
	v_lshlrev_b32_e32 v0, 1, v190
	v_and_b32_e32 v0, 0xfffffe00, v0
	v_add_u32_e32 v194, 0xfffffe00, v0
	v_ashrrev_i32_e32 v0, 2, v190
	v_and_b32_e32 v0, 0xfffffe00, v0
	v_add_u32_e32 v192, 0xffffce00, v0
	v_add_u32_e32 v193, 0xffffd200, v0
	v_and_b32_e32 v0, 0xfffff800, v190
	s_movk_i32 s0, 0xcc
	v_add_u32_e32 v191, 0xfffff000, v0
	v_bitop3_b32 v0, v190, s0, v188 bitop3:0xc8
	v_or_b32_e32 v164, v190, v188
	v_lshlrev_b32_e32 v0, 1, v0
	s_movk_i32 s0, 0x7cc
	v_ashrrev_i32_e32 v165, 31, v164
	v_lshl_add_u64 v[152:153], s[44:45], 0, v[0:1]
	v_bitop3_b32 v0, v190, s0, v188 bitop3:0xc8
	v_lshlrev_b64 v[144:145], 1, v[164:165]
	v_lshlrev_b64 v[136:137], 2, v[164:165]
	v_lshlrev_b32_e32 v0, 1, v0
	v_lshl_add_u64 v[138:139], s[36:37], 0, v[144:145]
	v_lshl_add_u64 v[142:143], s[40:41], 0, v[144:145]
	v_lshl_add_u64 v[140:141], s[42:43], 0, v[136:137]
	v_lshl_add_u64 v[148:149], s[48:49], 0, v[0:1]
	v_lshl_add_u64 v[150:151], s[50:51], 0, v[0:1]
	v_lshl_add_u64 v[146:147], s[52:53], 0, v[0:1]
	v_cmp_gt_i32_e64 s[8:9], s23, v164
	v_or_b32_e32 v130, s91, v189
	s_cmp_eq_u32 s90, 4
	s_cbranch_scc1 .Lepi4_start
	s_cmp_eq_u32 s90, 0
	s_cbranch_scc1 .Lepi0_start
	s_cmp_eq_u32 s90, 6
	s_cbranch_scc1 .Lepi6_start
	s_cmp_eq_u32 s90, 5
	s_cbranch_scc1 .Lepi5_start
	s_cmp_eq_u32 s90, 2
	s_cbranch_scc1 .Lepi2_start
	s_cmp_lt_i32 s90, 4
	s_mov_b64 s[0:1], -1
	s_cbranch_scc1 .LBB0_417
	s_cmp_lt_i32 s90, 6
	s_cbranch_scc1 .LBB0_411
	s_cmp_gt_i32 s90, 6
	s_cbranch_scc0 .LBB0_408
	v_add_u32_e32 v156, v194, v130
	v_ashrrev_i32_e32 v157, 31, v156
	v_lshlrev_b64 v[156:157], 9, v[156:157]
	v_lshl_add_u64 v[156:157], v[152:153], 0, v[156:157]
	v_cvt_pk_bf16_f32 v154,v126,v127
	v_cvt_pk_bf16_f32 v155,v128,v129
	flat_store_dwordx2 v[156:157], v[154:155]
	s_mov_b64 s[0:1], 0

; __device__ __forceinline__ void epilogue(const Params& p, int mode, const float* resid, int r, int c, f32x4 v) {
;   if (mode == EPI_PROJ) {
;     if (r >= INW) return;
;     u32x2 pk = {pk2(v[0], v[1]), pk2(v[2], v[3])};
;     *reinterpret_cast<u32x2*>(WSP(u16, WS_PROJB) + (long)c * INWP + r) = pk;
.Lepi0_start:
	v_lshrrev_b32_e32 v0, 2, v188
	v_lshrrev_b32_e32 v130, 2, v187
	v_or_b32_e32 v0, v0, v130
	v_and_b32_e32 v130, 15, v189
	v_lshlrev_b32_e32 v130, 1, v130
	v_xor_b32_e32 v0, v0, v130
	v_lshlrev_b32_e32 v0, 3, v0
	v_lshlrev_b32_e32 v131, 9, v189
	v_or_b32_e32 v136, v131, v0
	v_add_u32_e32 v136, 64, v136
	v_add_u32_e32 v140, 0x10000, v136
	v_xor_b32_e32 v130, 32, v0
	v_or_b32_e32 v137, v131, v130
	v_add_u32_e32 v137, 64, v137
	v_add_u32_e32 v141, 0x10000, v137
	v_xor_b32_e32 v130, 64, v0
	v_or_b32_e32 v138, v131, v130
	v_add_u32_e32 v138, 64, v138
	v_add_u32_e32 v142, 0x10000, v138
	v_xor_b32_e32 v130, 96, v0
	v_or_b32_e32 v139, v131, v130
	v_add_u32_e32 v139, 64, v139
	v_add_u32_e32 v143, 0x10000, v139
	v_cvt_pk_bf16_f32 v126, v126, v127
	v_cvt_pk_bf16_f32 v127, v128, v129
	ds_write_b64 v136, v[126:127] offset:0
	v_cvt_pk_bf16_f32 v122, v122, v123
	v_cvt_pk_bf16_f32 v123, v124, v125
	ds_write_b64 v136, v[122:123] offset:8192
	v_cvt_pk_bf16_f32 v118, v118, v119
	v_cvt_pk_bf16_f32 v119, v120, v121
	ds_write_b64 v137, v[118:119] offset:0
	v_cvt_pk_bf16_f32 v114, v114, v115
	v_cvt_pk_bf16_f32 v115, v116, v117
	ds_write_b64 v137, v[114:115] offset:8192
	v_cvt_pk_bf16_f32 v110, v110, v111
	v_cvt_pk_bf16_f32 v111, v112, v113
	ds_write_b64 v138, v[110:111] offset:0
	v_cvt_pk_bf16_f32 v106, v106, v107
	v_cvt_pk_bf16_f32 v107, v108, v109
	ds_write_b64 v138, v[106:107] offset:8192
	v_cvt_pk_bf16_f32 v102, v102, v103
	v_cvt_pk_bf16_f32 v103, v104, v105
	ds_write_b64 v139, v[102:103] offset:0
	v_cvt_pk_bf16_f32 v98, v98, v99
	v_cvt_pk_bf16_f32 v99, v100, v101
	ds_write_b64 v139, v[98:99] offset:8192
	v_cvt_pk_bf16_f32 v94, v94, v95
	v_cvt_pk_bf16_f32 v95, v96, v97
	ds_write_b64 v140, v[94:95] offset:0
	v_cvt_pk_bf16_f32 v90, v90, v91
	v_cvt_pk_bf16_f32 v91, v92, v93
	ds_write_b64 v140, v[90:91] offset:8192
	v_cvt_pk_bf16_f32 v86, v86, v87
	v_cvt_pk_bf16_f32 v87, v88, v89
	ds_write_b64 v141, v[86:87] offset:0
	v_cvt_pk_bf16_f32 v82, v82, v83
	v_cvt_pk_bf16_f32 v83, v84, v85
	ds_write_b64 v141, v[82:83] offset:8192
	v_cvt_pk_bf16_f32 v78, v78, v79
	v_cvt_pk_bf16_f32 v79, v80, v81
	ds_write_b64 v142, v[78:79] offset:0
	v_cvt_pk_bf16_f32 v74, v74, v75
	v_cvt_pk_bf16_f32 v75, v76, v77
	ds_write_b64 v142, v[74:75] offset:8192
	v_cvt_pk_bf16_f32 v70, v70, v71
	v_cvt_pk_bf16_f32 v71, v72, v73
	ds_write_b64 v143, v[70:71] offset:0
	v_cvt_pk_bf16_f32 v66, v66, v67
	v_cvt_pk_bf16_f32 v67, v68, v69
	ds_write_b64 v143, v[66:67] offset:8192
	v_cvt_pk_bf16_f32 v62, v62, v63
	v_cvt_pk_bf16_f32 v63, v64, v65
	ds_write_b64 v136, v[62:63] offset:256
	v_cvt_pk_bf16_f32 v58, v58, v59
	v_cvt_pk_bf16_f32 v59, v60, v61
	ds_write_b64 v136, v[58:59] offset:8448
	v_cvt_pk_bf16_f32 v54, v54, v55
	v_cvt_pk_bf16_f32 v55, v56, v57
	ds_write_b64 v137, v[54:55] offset:256
	v_cvt_pk_bf16_f32 v50, v50, v51
	v_cvt_pk_bf16_f32 v51, v52, v53
	ds_write_b64 v137, v[50:51] offset:8448
	v_cvt_pk_bf16_f32 v46, v46, v47
	v_cvt_pk_bf16_f32 v47, v48, v49
	ds_write_b64 v138, v[46:47] offset:256
	v_cvt_pk_bf16_f32 v42, v42, v43
	v_cvt_pk_bf16_f32 v43, v44, v45
	ds_write_b64 v138, v[42:43] offset:8448
	v_cvt_pk_bf16_f32 v38, v38, v39
	v_cvt_pk_bf16_f32 v39, v40, v41
	ds_write_b64 v139, v[38:39] offset:256
	v_cvt_pk_bf16_f32 v34, v34, v35
	v_cvt_pk_bf16_f32 v35, v36, v37
	ds_write_b64 v139, v[34:35] offset:8448
	v_cvt_pk_bf16_f32 v30, v30, v31
	v_cvt_pk_bf16_f32 v31, v32, v33
	ds_write_b64 v140, v[30:31] offset:256
	v_cvt_pk_bf16_f32 v26, v26, v27
	v_cvt_pk_bf16_f32 v27, v28, v29
	ds_write_b64 v140, v[26:27] offset:8448
	v_cvt_pk_bf16_f32 v22, v22, v23
	v_cvt_pk_bf16_f32 v23, v24, v25
	ds_write_b64 v141, v[22:23] offset:256
	v_cvt_pk_bf16_f32 v18, v18, v19
	v_cvt_pk_bf16_f32 v19, v20, v21
	ds_write_b64 v141, v[18:19] offset:8448
	v_cvt_pk_bf16_f32 v14, v14, v15
	v_cvt_pk_bf16_f32 v15, v16, v17
	ds_write_b64 v142, v[14:15] offset:256
	v_cvt_pk_bf16_f32 v10, v10, v11
	v_cvt_pk_bf16_f32 v11, v12, v13
	ds_write_b64 v142, v[10:11] offset:8448
	v_cvt_pk_bf16_f32 v6, v6, v7
	v_cvt_pk_bf16_f32 v7, v8, v9
	ds_write_b64 v143, v[6:7] offset:256
	v_cvt_pk_bf16_f32 v2, v2, v3
	v_cvt_pk_bf16_f32 v3, v4, v5
	ds_write_b64 v143, v[2:3] offset:8448
	v_lshrrev_b32_e32 v0, 2, v188
	v_lshrrev_b32_e32 v130, 1, v0
	v_and_b32_e32 v0, 1, v0
	v_lshlrev_b32_e32 v0, 4, v0
	v_and_b32_e32 v131, 15, v189
	v_or_b32_e32 v0, v0, v131
	v_lshrrev_b32_e32 v131, 4, v187
	v_lshrrev_b32_e32 v144, 5, v189
	v_or_b32_e32 v131, v131, v144
	v_lshl_or_b32 v131, v131, 5, v130
	v_xor_b32_e32 v144, v0, v130
	v_lshlrev_b32_e32 v144, 4, v144
	v_lshl_or_b32 v144, v131, 9, v144
	v_add_u32_e32 v131, s91, v131
	v_lshlrev_b32_e32 v130, 4, v0
	v_mad_u32_u24 v131, v131, s95, v130
	s_lshl_b32 s0, s74, 1
	v_add_u32_e32 v145, s0, v131
	v_lshl_add_u32 v130, v0, 3, s74
	v_cmp_gt_i32_e32 vcc, s23, v130
	s_mov_b64 s[8:9], s[36:37]
	v_mov_b32_e32 v146, v144
	v_xor_b32_e32 v147, 32, v144
	v_xor_b32_e32 v148, 64, v144
	v_xor_b32_e32 v149, 96, v144
	v_xor_b32_e32 v150, 128, v144
	v_xor_b32_e32 v151, 160, v144
	v_xor_b32_e32 v152, 192, v144
	v_xor_b32_e32 v153, 224, v144
	s_waitcnt lgkmcnt(0)
	s_barrier
; __device__ __forceinline__ void epilogue(const Params& p, int mode, const float* resid, int r, int c, f32x4 v) {
;   if (mode == EPI_PROJ) {
;     if (r >= INW) return;
;     u32x2 pk = {pk2(v[0], v[1]), pk2(v[2], v[3])};
;     *reinterpret_cast<u32x2*>(WSP(u16, WS_PROJB) + (long)c * INWP + r) = pk;
	ds_read_b128 v[2:5], v146 offset:64
	ds_read_b128 v[6:9], v147 offset:1088
	ds_read_b128 v[10:13], v148 offset:2112
	ds_read_b128 v[14:17], v149 offset:3136
	ds_read_b128 v[18:21], v150 offset:4160
	ds_read_b128 v[22:25], v151 offset:5184
	ds_read_b128 v[26:29], v152 offset:6208
	ds_read_b128 v[30:33], v153 offset:7232
	s_and_saveexec_b64 s[10:11], vcc
	s_waitcnt lgkmcnt(7)
	global_store_dwordx4 v145, v[2:5], s[8:9] nt
	s_add_u32 s8, s8, 0xd400
	s_addc_u32 s9, s9, 0
	ds_read_b128 v[34:37], v146 offset:8256
	s_waitcnt lgkmcnt(7)
	global_store_dwordx4 v145, v[6:9], s[8:9] nt
	s_add_u32 s8, s8, 0xd400
	s_addc_u32 s9, s9, 0
	ds_read_b128 v[38:41], v147 offset:9280
	s_waitcnt lgkmcnt(7)
	global_store_dwordx4 v145, v[10:13], s[8:9] nt
	s_add_u32 s8, s8, 0xd400
	s_addc_u32 s9, s9, 0
	ds_read_b128 v[42:45], v148 offset:10304
	s_waitcnt lgkmcnt(7)
	global_store_dwordx4 v145, v[14:17], s[8:9] nt
	s_add_u32 s8, s8, 0xd400
	s_addc_u32 s9, s9, 0
	ds_read_b128 v[46:49], v149 offset:11328
	s_waitcnt lgkmcnt(7)
	global_store_dwordx4 v145, v[18:21], s[8:9] nt
	s_add_u32 s8, s8, 0xd400
	s_addc_u32 s9, s9, 0
	ds_read_b128 v[50:53], v150 offset:12352
	s_waitcnt lgkmcnt(7)
	global_store_dwordx4 v145, v[22:25], s[8:9] nt
	s_add_u32 s8, s8, 0xd400
	s_addc_u32 s9, s9, 0
	ds_read_b128 v[54:57], v151 offset:13376
	s_waitcnt lgkmcnt(7)
	global_store_dwordx4 v145, v[26:29], s[8:9] nt
	s_add_u32 s8, s8, 0xd400
	s_addc_u32 s9, s9, 0
	ds_read_b128 v[58:61], v152 offset:14400
	s_waitcnt lgkmcnt(7)
	global_store_dwordx4 v145, v[30:33], s[8:9] nt
	s_add_u32 s8, s8, 0xd400
	s_addc_u32 s9, s9, 0
	ds_read_b128 v[62:65], v153 offset:15424
	s_waitcnt lgkmcnt(7)
	global_store_dwordx4 v145, v[34:37], s[8:9] nt
	s_add_u32 s8, s8, 0xd400
	s_addc_u32 s9, s9, 0
	s_waitcnt lgkmcnt(6)
	global_store_dwordx4 v145, v[38:41], s[8:9] nt
	s_add_u32 s8, s8, 0xd400
	s_addc_u32 s9, s9, 0
	s_waitcnt lgkmcnt(5)
	global_store_dwordx4 v145, v[42:45], s[8:9] nt
	s_add_u32 s8, s8, 0xd400
	s_addc_u32 s9, s9, 0
	s_waitcnt lgkmcnt(4)
	global_store_dwordx4 v145, v[46:49], s[8:9] nt
	s_add_u32 s8, s8, 0xd400
	s_addc_u32 s9, s9, 0
	s_waitcnt lgkmcnt(3)
	global_store_dwordx4 v145, v[50:53], s[8:9] nt
	s_add_u32 s8, s8, 0xd400
	s_addc_u32 s9, s9, 0
	s_waitcnt lgkmcnt(2)
	global_store_dwordx4 v145, v[54:57], s[8:9] nt
	s_add_u32 s8, s8, 0xd400
	s_addc_u32 s9, s9, 0
	s_waitcnt lgkmcnt(1)
	global_store_dwordx4 v145, v[58:61], s[8:9] nt
	s_add_u32 s8, s8, 0xd400
	s_addc_u32 s9, s9, 0
	s_waitcnt lgkmcnt(0)
	global_store_dwordx4 v145, v[62:65], s[8:9] nt
	s_add_u32 s8, s8, 0xd400
	s_addc_u32 s9, s9, 0
	s_mov_b64 exec, s[10:11]
	s_waitcnt lgkmcnt(0)
	s_barrier
	s_branch .LBB0_382
; __device__ __forceinline__ void epilogue(const Params& p, int mode, const float* resid, int r, int c, f32x4 v) {
;     ...
;   } else if (mode == EPI_PROJ_T) {
;     const int b = r >> 11, t = r & 2047;
;     u16* tp;
;     if (c < OFF_RG) tp = WSP(u16, WS_RVT) + ((long)(b * 2048 + c - OFF_RV)) * 2048 + t;
;     else if (c < OFF_KW) tp = WSP(u16, WS_VST) + ((long)(b * 512 + c - OFF_VS)) * 2048 + t;
;     else tp = WSP(u16, WS_VWT) + ((long)(b * 512 + c - OFF_VW)) * 2048 + t;
;     *reinterpret_cast<u32x2*>(tp) = u32x2{pk2(v[0], v[1]), pk2(v[2], v[3])};
.Lepi6_start:
	v_lshrrev_b32_e32 v0, 2, v188
	v_lshrrev_b32_e32 v130, 2, v187
	v_or_b32_e32 v0, v0, v130
	v_and_b32_e32 v130, 15, v189
	v_lshlrev_b32_e32 v130, 1, v130
	v_xor_b32_e32 v0, v0, v130
	v_lshlrev_b32_e32 v0, 3, v0
	v_lshlrev_b32_e32 v131, 9, v189
	v_or_b32_e32 v136, v131, v0
	v_add_u32_e32 v136, 64, v136
	v_add_u32_e32 v140, 0x10000, v136
	v_xor_b32_e32 v130, 32, v0
	v_or_b32_e32 v137, v131, v130
	v_add_u32_e32 v137, 64, v137
	v_add_u32_e32 v141, 0x10000, v137
	v_xor_b32_e32 v130, 64, v0
	v_or_b32_e32 v138, v131, v130
	v_add_u32_e32 v138, 64, v138
	v_add_u32_e32 v142, 0x10000, v138
	v_xor_b32_e32 v130, 96, v0
	v_or_b32_e32 v139, v131, v130
	v_add_u32_e32 v139, 64, v139
	v_add_u32_e32 v143, 0x10000, v139
	v_cvt_pk_bf16_f32 v126, v126, v127
	v_cvt_pk_bf16_f32 v127, v128, v129
	ds_write_b64 v136, v[126:127] offset:0
	v_cvt_pk_bf16_f32 v122, v122, v123
	v_cvt_pk_bf16_f32 v123, v124, v125
	ds_write_b64 v136, v[122:123] offset:8192
	v_cvt_pk_bf16_f32 v118, v118, v119
	v_cvt_pk_bf16_f32 v119, v120, v121
	ds_write_b64 v137, v[118:119] offset:0
	v_cvt_pk_bf16_f32 v114, v114, v115
	v_cvt_pk_bf16_f32 v115, v116, v117
	ds_write_b64 v137, v[114:115] offset:8192
	v_cvt_pk_bf16_f32 v110, v110, v111
	v_cvt_pk_bf16_f32 v111, v112, v113
	ds_write_b64 v138, v[110:111] offset:0
	v_cvt_pk_bf16_f32 v106, v106, v107
	v_cvt_pk_bf16_f32 v107, v108, v109
	ds_write_b64 v138, v[106:107] offset:8192
	v_cvt_pk_bf16_f32 v102, v102, v103
	v_cvt_pk_bf16_f32 v103, v104, v105
	ds_write_b64 v139, v[102:103] offset:0
	v_cvt_pk_bf16_f32 v98, v98, v99
	v_cvt_pk_bf16_f32 v99, v100, v101
	ds_write_b64 v139, v[98:99] offset:8192
	v_cvt_pk_bf16_f32 v94, v94, v95
	v_cvt_pk_bf16_f32 v95, v96, v97
	ds_write_b64 v140, v[94:95] offset:0
	v_cvt_pk_bf16_f32 v90, v90, v91
	v_cvt_pk_bf16_f32 v91, v92, v93
	ds_write_b64 v140, v[90:91] offset:8192
	v_cvt_pk_bf16_f32 v86, v86, v87
	v_cvt_pk_bf16_f32 v87, v88, v89
	ds_write_b64 v141, v[86:87] offset:0
	v_cvt_pk_bf16_f32 v82, v82, v83
	v_cvt_pk_bf16_f32 v83, v84, v85
	ds_write_b64 v141, v[82:83] offset:8192
	v_cvt_pk_bf16_f32 v78, v78, v79
	v_cvt_pk_bf16_f32 v79, v80, v81
	ds_write_b64 v142, v[78:79] offset:0
	v_cvt_pk_bf16_f32 v74, v74, v75
	v_cvt_pk_bf16_f32 v75, v76, v77
	ds_write_b64 v142, v[74:75] offset:8192
	v_cvt_pk_bf16_f32 v70, v70, v71
	v_cvt_pk_bf16_f32 v71, v72, v73
	ds_write_b64 v143, v[70:71] offset:0
	v_cvt_pk_bf16_f32 v66, v66, v67
	v_cvt_pk_bf16_f32 v67, v68, v69
	ds_write_b64 v143, v[66:67] offset:8192
	v_cvt_pk_bf16_f32 v62, v62, v63
	v_cvt_pk_bf16_f32 v63, v64, v65
	ds_write_b64 v136, v[62:63] offset:256
	v_cvt_pk_bf16_f32 v58, v58, v59
	v_cvt_pk_bf16_f32 v59, v60, v61
	ds_write_b64 v136, v[58:59] offset:8448
	v_cvt_pk_bf16_f32 v54, v54, v55
	v_cvt_pk_bf16_f32 v55, v56, v57
	ds_write_b64 v137, v[54:55] offset:256
	v_cvt_pk_bf16_f32 v50, v50, v51
	v_cvt_pk_bf16_f32 v51, v52, v53
	ds_write_b64 v137, v[50:51] offset:8448
	v_cvt_pk_bf16_f32 v46, v46, v47
	v_cvt_pk_bf16_f32 v47, v48, v49
	ds_write_b64 v138, v[46:47] offset:256
	v_cvt_pk_bf16_f32 v42, v42, v43
	v_cvt_pk_bf16_f32 v43, v44, v45
	ds_write_b64 v138, v[42:43] offset:8448
	v_cvt_pk_bf16_f32 v38, v38, v39
	v_cvt_pk_bf16_f32 v39, v40, v41
	ds_write_b64 v139, v[38:39] offset:256
	v_cvt_pk_bf16_f32 v34, v34, v35
	v_cvt_pk_bf16_f32 v35, v36, v37
	ds_write_b64 v139, v[34:35] offset:8448
	v_cvt_pk_bf16_f32 v30, v30, v31
	v_cvt_pk_bf16_f32 v31, v32, v33
	ds_write_b64 v140, v[30:31] offset:256
	v_cvt_pk_bf16_f32 v26, v26, v27
	v_cvt_pk_bf16_f32 v27, v28, v29
	ds_write_b64 v140, v[26:27] offset:8448
	v_cvt_pk_bf16_f32 v22, v22, v23
	v_cvt_pk_bf16_f32 v23, v24, v25
	ds_write_b64 v141, v[22:23] offset:256
	v_cvt_pk_bf16_f32 v18, v18, v19
	v_cvt_pk_bf16_f32 v19, v20, v21
	ds_write_b64 v141, v[18:19] offset:8448
	v_cvt_pk_bf16_f32 v14, v14, v15
	v_cvt_pk_bf16_f32 v15, v16, v17
	ds_write_b64 v142, v[14:15] offset:256
	v_cvt_pk_bf16_f32 v10, v10, v11
	v_cvt_pk_bf16_f32 v11, v12, v13
	ds_write_b64 v142, v[10:11] offset:8448
	v_cvt_pk_bf16_f32 v6, v6, v7
	v_cvt_pk_bf16_f32 v7, v8, v9
	ds_write_b64 v143, v[6:7] offset:256
	v_cvt_pk_bf16_f32 v2, v2, v3
	v_cvt_pk_bf16_f32 v3, v4, v5
	ds_write_b64 v143, v[2:3] offset:8448
	v_lshrrev_b32_e32 v0, 2, v188
	v_lshrrev_b32_e32 v130, 1, v0
	v_and_b32_e32 v0, 1, v0
	v_lshlrev_b32_e32 v0, 4, v0
	v_and_b32_e32 v131, 15, v189
	v_or_b32_e32 v0, v0, v131
	v_lshrrev_b32_e32 v131, 4, v187
	v_lshrrev_b32_e32 v144, 5, v189
	v_or_b32_e32 v131, v131, v144
	v_lshl_or_b32 v131, v131, 5, v130
	v_xor_b32_e32 v144, v0, v130
	v_lshlrev_b32_e32 v144, 4, v144
	v_lshl_or_b32 v144, v131, 9, v144
	s_lshr_b32 s0, s74, 11
	s_cmpk_lt_u32 s91, 0x1800
	s_cbranch_scc1 .Lepi6_rvt
	s_lshl_b32 s0, s0, 9
	s_cmpk_lt_u32 s91, 0x3000
	s_cbranch_scc1 .Lepi6_vst
	s_sub_i32 s0, s0, 0x3200
	s_mov_b64 s[8:9], s[48:49]
	s_branch .Lepi6_go

; __device__ __forceinline__ void epilogue(const Params& p, int mode, const float* resid, int r, int c, f32x4 v) {
;     ...
;   } else if (mode == EPI_PROJ_T) {
;     const int b = r >> 11, t = r & 2047;
;     u16* tp;
;     if (c < OFF_RG) tp = WSP(u16, WS_RVT) + ((long)(b * 2048 + c - OFF_RV)) * 2048 + t;
;     else if (c < OFF_KW) tp = WSP(u16, WS_VST) + ((long)(b * 512 + c - OFF_VS)) * 2048 + t;
;     else tp = WSP(u16, WS_VWT) + ((long)(b * 512 + c - OFF_VW)) * 2048 + t;
;     *reinterpret_cast<u32x2*>(tp) = u32x2{pk2(v[0], v[1]), pk2(v[2], v[3])};
.Lepi6_go:
	s_add_i32 s0, s0, s91
	v_add_u32_e32 v131, s0, v131
	v_lshlrev_b32_e32 v131, 12, v131
	v_lshl_add_u32 v131, v0, 4, v131
	s_and_b32 s0, s74, 0x7ff
	s_lshl_b32 s0, s0, 1
	v_add_u32_e32 v145, s0, v131
	v_mov_b32_e32 v146, v144
	v_xor_b32_e32 v147, 32, v144
	v_xor_b32_e32 v148, 64, v144
	v_xor_b32_e32 v149, 96, v144
	v_xor_b32_e32 v150, 128, v144
	v_xor_b32_e32 v151, 160, v144
	v_xor_b32_e32 v152, 192, v144
	v_xor_b32_e32 v153, 224, v144
	s_waitcnt lgkmcnt(0)
	s_barrier
	ds_read_b128 v[2:5], v146 offset:64
	ds_read_b128 v[6:9], v147 offset:1088
	ds_read_b128 v[10:13], v148 offset:2112
	ds_read_b128 v[14:17], v149 offset:3136
	ds_read_b128 v[18:21], v150 offset:4160
	ds_read_b128 v[22:25], v151 offset:5184
	ds_read_b128 v[26:29], v152 offset:6208
	ds_read_b128 v[30:33], v153 offset:7232
	s_waitcnt lgkmcnt(7)
	global_store_dwordx4 v145, v[2:5], s[8:9] nt
	s_add_u32 s8, s8, 0x2000
	s_addc_u32 s9, s9, 0
	ds_read_b128 v[34:37], v146 offset:8256
	s_waitcnt lgkmcnt(7)
	global_store_dwordx4 v145, v[6:9], s[8:9] nt
	s_add_u32 s8, s8, 0x2000
	s_addc_u32 s9, s9, 0
	ds_read_b128 v[38:41], v147 offset:9280
	s_waitcnt lgkmcnt(7)
	global_store_dwordx4 v145, v[10:13], s[8:9] nt
	s_add_u32 s8, s8, 0x2000
	s_addc_u32 s9, s9, 0
	ds_read_b128 v[42:45], v148 offset:10304
	s_waitcnt lgkmcnt(7)
	global_store_dwordx4 v145, v[14:17], s[8:9] nt
	s_add_u32 s8, s8, 0x2000
	s_addc_u32 s9, s9, 0
	ds_read_b128 v[46:49], v149 offset:11328
	s_waitcnt lgkmcnt(7)
	global_store_dwordx4 v145, v[18:21], s[8:9] nt
	s_add_u32 s8, s8, 0x2000
	s_addc_u32 s9, s9, 0
	ds_read_b128 v[50:53], v150 offset:12352
	s_waitcnt lgkmcnt(7)
	global_store_dwordx4 v145, v[22:25], s[8:9] nt
	s_add_u32 s8, s8, 0x2000
	s_addc_u32 s9, s9, 0
	ds_read_b128 v[54:57], v151 offset:13376
	s_waitcnt lgkmcnt(7)
	global_store_dwordx4 v145, v[26:29], s[8:9] nt
	s_add_u32 s8, s8, 0x2000
	s_addc_u32 s9, s9, 0
	ds_read_b128 v[58:61], v152 offset:14400
	s_waitcnt lgkmcnt(7)
	global_store_dwordx4 v145, v[30:33], s[8:9] nt
	s_add_u32 s8, s8, 0x2000
	s_addc_u32 s9, s9, 0
	ds_read_b128 v[62:65], v153 offset:15424
	s_waitcnt lgkmcnt(7)
	global_store_dwordx4 v145, v[34:37], s[8:9] nt
	s_add_u32 s8, s8, 0x2000
	s_addc_u32 s9, s9, 0
	s_waitcnt lgkmcnt(6)
	global_store_dwordx4 v145, v[38:41], s[8:9] nt
	s_add_u32 s8, s8, 0x2000
	s_addc_u32 s9, s9, 0
	s_waitcnt lgkmcnt(5)
	global_store_dwordx4 v145, v[42:45], s[8:9] nt
	s_add_u32 s8, s8, 0x2000
	s_addc_u32 s9, s9, 0
	s_waitcnt lgkmcnt(4)
	global_store_dwordx4 v145, v[46:49], s[8:9] nt
	s_add_u32 s8, s8, 0x2000
	s_addc_u32 s9, s9, 0
	s_waitcnt lgkmcnt(3)
	global_store_dwordx4 v145, v[50:53], s[8:9] nt
	s_add_u32 s8, s8, 0x2000
	s_addc_u32 s9, s9, 0
	s_waitcnt lgkmcnt(2)
	global_store_dwordx4 v145, v[54:57], s[8:9] nt
	s_add_u32 s8, s8, 0x2000
	s_addc_u32 s9, s9, 0
	s_waitcnt lgkmcnt(1)
	global_store_dwordx4 v145, v[58:61], s[8:9] nt
	s_add_u32 s8, s8, 0x2000
	s_addc_u32 s9, s9, 0
	s_waitcnt lgkmcnt(0)
	global_store_dwordx4 v145, v[62:65], s[8:9] nt
	s_add_u32 s8, s8, 0x2000
	s_addc_u32 s9, s9, 0
	s_waitcnt lgkmcnt(0)
	s_barrier
	s_branch .LBB0_382
